# pre-pass trimmed: BUFM jobs moved to the P1c idle slot (v046) and the HG zero-fill spread over all workgroups instead of workgroup 0 alone
# baseline (speedup 1.0000x reference)
; __device__ __forceinline__ void phase_colmax(const Params& p, LAS unsigned char* lds) {
;     ...
;     if (blockIdx.x == 0) { u32x4 z = (u32x4){0u, 0u, 0u, 0u}; u32x4* hg = (u32x4*)(p.ws + WS_HG + (size_t)72 * LDP * 2);
;         for (int i = threadIdx.x; i < (256 - 72) * LDP * 2 / 16; i += NTHREADS) hg[i] = z; }
; __device__ __forceinline__ void xcd_barrier(const XcdBarrier& b) {
;     asm volatile("s_waitcnt vmcnt(0)" ::: "memory");
;     __syncthreads();
;     if (threadIdx.x == 0) {
;         unsigned* bar = b.bar;
;         __builtin_amdgcn_s_waitcnt(0);
;         unsigned nloc = b.st[0], nx = b.st[1];
;         if (nloc == 0u) { xcd_barrier_complete(bar, b.x, nloc, nx); b.st[0] = nloc; b.st[1] = nx; }
.LBB0_74:
	v_lshl_add_u32 v1, s8, 9, v0
	v_mov_b32_e32 v3, 0
	v_cmp_gt_u32_e32 vcc, 0xbdc0, v1
	s_and_saveexec_b64 s[2:3], vcc
	s_cbranch_execz .Lhgz_done
	v_lshlrev_b32_e32 v2, 4, v1
	v_lshl_add_u64 v[4:5], s[26:27], 0, v[2:3]
	s_mov_b64 s[0:1], 0x39681400
	v_lshl_add_u64 v[6:7], v[4:5], 0, s[0:1]
	v_mov_b32_e32 v2, v3
	v_mov_b32_e32 v4, v3
	v_mov_b32_e32 v5, v3
	global_store_dwordx4 v[6:7], v[2:5], off
.Lhgz_done:
	s_or_b64 exec, exec, s[2:3]
.LBB0_78:
	s_waitcnt vmcnt(0)
	s_barrier
	s_mov_b64 s[2:3], exec
	v_readlane_b32 s0, v230, 3
	v_readlane_b32 s1, v230, 4
	s_and_b64 s[0:1], s[2:3], s[0:1]
	s_mov_b64 exec, s[0:1]
	s_cbranch_execz .LBB0_130
	s_add_i32 s0, 0, 0x20000
	v_mov_b32_e32 v1, s0
	s_waitcnt vmcnt(0) expcnt(0) lgkmcnt(0)
	ds_read_b32 v3, v1
	s_add_i32 s0, 0, 0x20004
	v_mov_b32_e32 v1, s0
	ds_read_b32 v1, v1
	s_waitcnt lgkmcnt(1)
	v_cmp_ne_u32_e32 vcc, 0, v3
	s_cbranch_vccnz .LBB0_94
	v_readlane_b32 s4, v230, 0
	v_readlane_b32 s5, v230, 1
	s_load_dwordx2 s[0:1], s[4:5], 0x4
	s_add_u32 s4, s26, 0x2f040200
	s_addc_u32 s5, s27, 0
	s_add_u32 s6, s26, 0x2f040400
	s_addc_u32 s7, s27, 0
	s_add_u32 s30, s26, 0x2f040500
	s_addc_u32 s31, s27, 0
	s_add_u32 s40, s26, 0x2f040600
	s_addc_u32 s41, s27, 0
	s_add_u32 s50, s26, 0x2f040700
	s_addc_u32 s51, s27, 0
	s_add_u32 s52, s26, 0x2f040800
	s_addc_u32 s53, s27, 0
	s_add_u32 s54, s26, 0x2f040900
	s_addc_u32 s55, s27, 0
	s_add_u32 s56, s26, 0x2f040a00
	s_addc_u32 s57, s27, 0
	s_add_u32 s58, s26, 0x2f040b00
	s_addc_u32 s59, s27, 0
	s_add_u32 s60, s26, 0x2f040c00
	s_addc_u32 s61, s27, 0
	s_add_u32 s62, s26, 0x2f040d00
	s_addc_u32 s63, s27, 0
	s_add_u32 s64, s26, 0x2f040e00
	s_addc_u32 s65, s27, 0
	s_add_u32 s66, s26, 0x2f040f00
	s_addc_u32 s67, s27, 0
	s_add_u32 s68, s26, 0x2f041000
	s_addc_u32 s69, s27, 0
	s_add_u32 s70, s26, 0x2f041100
	s_addc_u32 s71, s27, 0
	s_add_u32 s72, s26, 0x2f041200
	s_addc_u32 s73, s27, 0
	s_waitcnt lgkmcnt(0)
	s_mul_i32 s0, s0, s33
	s_add_u32 s74, s26, 0x2f041300
	s_mul_i32 s0, s0, s1
	s_addc_u32 s75, s27, 0
	s_mov_b32 s1, 1
	v_mov_b32_e32 v17, 0
	s_branch .LBB0_82
